# v33 + lat phase work queue reordered: 448 up-projection tiles first, 128 short rotary-key units last as tail filler
# speedup vs baseline: 1.0056x; 1.0051x over previous
; DI int tid() { int t = threadIdx.x; asm volatile("" : "+v"(t)); return t; }
; DI void lat_tile(const Params& p, int l, int T, char* lds) {
;     ...
;     const int T2 = T - 192;
;     const int mi = T2 & 31, ni = T2 >> 5, m0 = mi * 256, n0 = ni * 256;
;     const u16* A = p.CKV + (size_t)m0 * 512;
;     const u16* Bt = p.WukvT + ((size_t)l * 2048 + n0) * 512;
;     if (ni >= 4) {
;       gemm_main<false, true>(A, 512, Bt, 512, 512, lds, acc, rs);
;       epi_vt(acc, p.VBT, n0 - 1024, m0, rs);
;     } else {
;       gemm_main<true, true>(A, 512, Bt, 512, 512, lds, acc, rs);
; DI void phase_lat(const Params& p, int l, char* lds) {
;     ...
;   for (;;) {
;     __syncthreads();
;     if (tid() == 0) *ubox = (int)atomicAdd(ctr, 1u);
;     __syncthreads();
;     const int u = *ubox;
;     if (u >= 128 + 448) break;
;     if (u < 128) kr_unit(p, l, u, lds); else lat_tile(p, l, u - 128, lds);
.LBB0_140:
	s_or_b64 exec, exec, s[0:1]
	s_waitcnt lgkmcnt(0)
	s_barrier
	ds_read_b32 v0, v224
	s_movk_i32 s0, 0x23f
	s_waitcnt lgkmcnt(0)
	v_cmp_lt_i32_e32 vcc, s0, v0
	v_readfirstlane_b32 s52, v0
	s_mov_b64 s[0:1], -1
	s_cbranch_vccnz .LBB0_135
	s_add_i32 s52, s52, 0x80
	s_cmp_gt_i32 s52, 0x23f
	s_cbranch_scc0 .Llat_remap_ok
	s_sub_i32 s52, s52, 0x240
.Llat_remap_ok:
	s_cmpk_gt_i32 s52, 0x7f
	s_cbranch_scc0 .LBB0_197
	s_add_i32 s53, s52, 0xffffff80
	v_mov_b32_e32 v0, v222
	s_cmpk_gt_u32 s53, 0xbf
	v_bfe_u32 v176, v0, 6, 2
	s_cbranch_scc0 .LBB0_176
	s_add_i32 s0, s52, 0xfffffec0
	s_lshl_b32 s1, s53, 8
	s_and_b32 s2, s1, 0x1f00
	s_lshl_b32 s1, s0, 3
	s_and_b32 s4, s1, 0x7fffff00
	s_lshl_b32 s1, s2, 10
	s_add_u32 s92, s20, s1
	s_addc_u32 s93, s21, 0
	s_lshl_b64 s[90:91], s[4:5], 10
	s_add_u32 s94, s62, s90
	s_addc_u32 s95, s63, s91
	s_cmpk_lt_u32 s0, 0x80
	s_mov_b64 s[0:1], -1
	s_cbranch_scc0 .LBB0_159
	v_mov_b32_e32 v50, v222
	s_mov_b32 s96, 0
	v_ashrrev_i32_e32 v162, 3, v50
	v_ashrrev_i32_e32 v163, 31, v162
	v_and_b32_e32 v177, 7, v50
	v_lshlrev_b64 v[34:35], 10, v[162:163]
	v_lshl_add_u64 v[4:5], s[92:93], 0, v[34:35]
	v_lshlrev_b32_e32 v0, 4, v177
	v_lshl_add_u64 v[164:165], v[4:5], 0, v[0:1]
	v_lshl_add_u64 v[2:3], s[94:95], 0, v[34:35]
	v_add_co_u32_e32 v38, vcc, s72, v164
	v_lshl_add_u64 v[36:37], v[2:3], 0, v[0:1]
	s_nop 0
	v_addc_co_u32_e32 v39, vcc, 0, v165, vcc
	v_add_co_u32_e32 v40, vcc, s72, v36
	global_load_dwordx4 v[2:5], v[164:165], off
	global_load_dwordx4 v[6:9], v[36:37], off
	v_addc_co_u32_e32 v41, vcc, 0, v37, vcc
	v_add_co_u32_e32 v42, vcc, s73, v164
	global_load_dwordx4 v[10:13], v[38:39], off
	s_nop 0
	v_addc_co_u32_e32 v43, vcc, 0, v165, vcc
	v_add_co_u32_e32 v44, vcc, s73, v36
	global_load_dwordx4 v[18:21], v[42:43], off
	s_nop 0
	v_addc_co_u32_e32 v45, vcc, 0, v37, vcc
	v_add_co_u32_e32 v46, vcc, s59, v164
	global_load_dwordx4 v[14:17], v[40:41], off
	s_nop 0
	v_addc_co_u32_e32 v47, vcc, 0, v165, vcc
	global_load_dwordx4 v[22:25], v[44:45], off
	v_add_co_u32_e32 v48, vcc, s59, v36
	global_load_dwordx4 v[26:29], v[46:47], off
	s_nop 0
	v_addc_co_u32_e32 v49, vcc, 0, v37, vcc
	global_load_dwordx4 v[30:33], v[48:49], off
	v_mad_u64_u32 v[168:169], s[0:1], v162, s9, v[0:1]
	s_barrier
; #define G_LOAD(KT) do { const int k0_ = (KT) << 6; _Pragma("unroll") for (int p = 0; p < 4; ++p) { \
;     ra[p] = *(const u32x4*)(ap + (size_t)(64 * p) * lda + k0_); rb[p] = *(const u32x4*)(bp + (size_t)(64 * p) * ldb + k0_); } } while (0)
; template <bool SWAP, bool SSQ, bool ZERO = true>
; DI void gemm_main(const u16* __restrict__ A, int lda, const u16* __restrict__ Bt, int ldb, int K, char* lds,
;                   f32x16 (&acc)[4][2], float* rs_lds) {
;     ...
;   float ssq[4] = {0.f, 0.f, 0.f, 0.f};
;   if (ZERO) {
; #pragma unroll
;     for (int mt = 0; mt < 4; ++mt)
; #pragma unroll
;       for (int nt = 0; nt < 2; ++nt)
; #pragma unroll
;         for (int i = 0; i < 16; ++i) acc[mt][nt][i] = 0.f;
;   }
;   const int nk = K >> 6;
;   char* const wbase = lds + lr * GS + lc * 16;
;   const char* abase = lds + (wm * 128 + r) * GS + hf * 16;
;   const char* bbase = lds + G_TILE + (wn * 64 + r) * GS + hf * 16;
;     ...
;   G_LOAD(0);
;   __syncthreads();
;   G_WRITE(0);
;   G_LOAD(1);
;   __syncthreads();
	v_and_b32_e32 v51, 31, v50
	v_lshrrev_b32_e32 v52, 1, v50
	v_and_b32_e32 v60, 0xdf, v50
	v_and_or_b32 v51, v52, s7, v51
	v_and_b32_e32 v50, 16, v52
	v_mad_u64_u32 v[170:171], s[0:1], v51, s9, v[50:51]
	v_readlane_b32 s0, v241, 34
	v_readlane_b32 s1, v241, 35
	v_mad_u32_u24 v163, v60, s9, v50
	s_mov_b32 s97, 2
	s_waitcnt vmcnt(7)
	ds_write_b128 v168, v[2:5]
	s_waitcnt vmcnt(6)
	ds_write_b128 v168, v[6:9] offset:36864
	s_waitcnt vmcnt(5)
	ds_write_b128 v168, v[10:13] offset:9216
	s_waitcnt vmcnt(3)
	ds_write_b128 v168, v[14:17] offset:46080
	ds_write_b128 v168, v[18:21] offset:18432
	s_waitcnt vmcnt(2)
	ds_write_b128 v168, v[22:25] offset:55296
	s_waitcnt vmcnt(1)
	ds_write_b128 v168, v[26:29] offset:27648
	s_waitcnt vmcnt(0)
	ds_write_b128 v168, v[30:33] offset:64512
	global_load_dwordx4 v[130:133], v[164:165], off offset:128
	global_load_dwordx4 v[134:137], v[36:37], off offset:128
	global_load_dwordx4 v[138:141], v[38:39], off offset:128
	global_load_dwordx4 v[142:145], v[40:41], off offset:128
	global_load_dwordx4 v[146:149], v[42:43], off offset:128
	global_load_dwordx4 v[150:153], v[44:45], off offset:128
	global_load_dwordx4 v[154:157], v[46:47], off offset:128
	global_load_dwordx4 v[158:161], v[48:49], off offset:128
	v_lshlrev_b32_e32 v6, 16, v2
	v_lshlrev_b32_e32 v7, 16, v10
	v_and_b32_e32 v2, 0xffff0000, v2
	v_lshlrev_b32_e32 v8, 16, v3
	v_and_b32_e32 v52, 0xffff0000, v3
	v_and_b32_e32 v3, 0xffff0000, v10
	v_pk_fma_f32 v[6:7], v[6:7], v[6:7], 0 op_sel_hi:[1,1,0]
	v_lshlrev_b32_e32 v9, 16, v11
	v_pk_fma_f32 v[2:3], v[2:3], v[2:3], v[6:7]
	v_and_b32_e32 v53, 0xffff0000, v11
	v_lshlrev_b32_e32 v11, 16, v26
	v_lshlrev_b32_e32 v10, 16, v18
	v_pk_fma_f32 v[2:3], v[8:9], v[8:9], v[2:3]
	v_lshlrev_b32_e32 v54, 16, v4
	v_lshlrev_b32_e32 v56, 16, v5
	v_and_b32_e32 v58, 0xffff0000, v5
	v_lshlrev_b32_e32 v55, 16, v12
	v_and_b32_e32 v5, 0xffff0000, v12
	v_lshlrev_b32_e32 v57, 16, v13
	v_and_b32_e32 v59, 0xffff0000, v13
	v_and_b32_e32 v13, 0xffff0000, v26
	v_and_b32_e32 v12, 0xffff0000, v18
	v_pk_fma_f32 v[10:11], v[10:11], v[10:11], 0 op_sel_hi:[1,1,0]
	v_pk_fma_f32 v[2:3], v[52:53], v[52:53], v[2:3]
	v_and_b32_e32 v4, 0xffff0000, v4
	v_lshlrev_b32_e32 v15, 16, v27
	v_lshlrev_b32_e32 v14, 16, v19
	v_pk_fma_f32 v[10:11], v[12:13], v[12:13], v[10:11]
	v_pk_fma_f32 v[2:3], v[54:55], v[54:55], v[2:3]
	v_and_b32_e32 v17, 0xffff0000, v27
	v_and_b32_e32 v16, 0xffff0000, v19
	v_pk_fma_f32 v[6:7], v[14:15], v[14:15], v[10:11]
	v_pk_fma_f32 v[2:3], v[4:5], v[4:5], v[2:3]
	v_lshlrev_b32_e32 v19, 16, v28
	v_lshlrev_b32_e32 v18, 16, v20
	v_pk_fma_f32 v[6:7], v[16:17], v[16:17], v[6:7]
	v_pk_fma_f32 v[2:3], v[56:57], v[56:57], v[2:3]
	v_and_b32_e32 v23, 0xffff0000, v28
	v_and_b32_e32 v22, 0xffff0000, v20
	v_pk_fma_f32 v[6:7], v[18:19], v[18:19], v[6:7]
	v_pk_fma_f32 v[172:173], v[58:59], v[58:59], v[2:3]
	v_lshl_add_u64 v[2:3], s[90:91], 0, v[34:35]
	v_lshlrev_b32_e32 v25, 16, v29
	v_lshlrev_b32_e32 v24, 16, v21
	v_pk_fma_f32 v[6:7], v[22:23], v[22:23], v[6:7]
	v_lshl_add_u64 v[2:3], v[2:3], 0, v[0:1]
	v_and_b32_e32 v27, 0xffff0000, v29
	v_and_b32_e32 v26, 0xffff0000, v21
	v_pk_fma_f32 v[4:5], v[24:25], v[24:25], v[6:7]
	v_lshl_add_u64 v[174:175], s[0:1], 0, v[2:3]
	v_mov_b32_e32 v2, 0
	v_pk_fma_f32 v[166:167], v[26:27], v[26:27], v[4:5]
	s_mov_b64 s[0:1], 0
	v_mov_b32_e32 v3, v2
	v_mov_b32_e32 v4, v2
	v_mov_b32_e32 v5, v2
	v_mov_b32_e32 v6, v2
	v_mov_b32_e32 v7, v2
	v_mov_b32_e32 v8, v2
	v_mov_b32_e32 v9, v2
	v_mov_b32_e32 v10, v2
	v_mov_b32_e32 v11, v2
	v_mov_b32_e32 v12, v2
	v_mov_b32_e32 v13, v2
	v_mov_b32_e32 v14, v2
	v_mov_b32_e32 v15, v2
	v_mov_b32_e32 v16, v2
	v_mov_b32_e32 v17, v2
	v_mov_b32_e32 v18, v2
	v_mov_b32_e32 v19, v2
	v_mov_b32_e32 v20, v2
	v_mov_b32_e32 v21, v2
	v_mov_b32_e32 v22, v2
	v_mov_b32_e32 v23, v2
	v_mov_b32_e32 v24, v2
	v_mov_b32_e32 v25, v2
	v_mov_b32_e32 v26, v2
	v_mov_b32_e32 v27, v2
	v_mov_b32_e32 v28, v2
	v_mov_b32_e32 v29, v2
	v_mov_b32_e32 v30, v2
	v_mov_b32_e32 v31, v2
	v_mov_b32_e32 v32, v2
	v_mov_b32_e32 v33, v2
	v_mov_b32_e32 v34, v2
	v_mov_b32_e32 v35, v2
	v_mov_b32_e32 v36, v2
	v_mov_b32_e32 v37, v2
	v_mov_b32_e32 v38, v2
	v_mov_b32_e32 v39, v2
	v_mov_b32_e32 v40, v2
	v_mov_b32_e32 v41, v2
	v_mov_b32_e32 v42, v2
	v_mov_b32_e32 v43, v2
	v_mov_b32_e32 v44, v2
	v_mov_b32_e32 v45, v2
	v_mov_b32_e32 v46, v2
	v_mov_b32_e32 v47, v2
	v_mov_b32_e32 v48, v2
	v_mov_b32_e32 v49, v2
	v_mov_b32_e32 v50, v2
	v_mov_b32_e32 v51, v2
	v_mov_b32_e32 v52, v2
	v_mov_b32_e32 v53, v2
	v_mov_b32_e32 v54, v2
	v_mov_b32_e32 v55, v2
	v_mov_b32_e32 v56, v2
	v_mov_b32_e32 v57, v2
	v_mov_b32_e32 v58, v2
	v_mov_b32_e32 v59, v2
	v_mov_b32_e32 v60, v2
	v_mov_b32_e32 v61, v2
	v_mov_b32_e32 v62, v2
	v_mov_b32_e32 v63, v2
	v_mov_b32_e32 v64, v2
	v_mov_b32_e32 v65, v2
	v_mov_b32_e32 v66, v2
	v_mov_b32_e32 v67, v2
	v_mov_b32_e32 v68, v2
	v_mov_b32_e32 v69, v2
	v_mov_b32_e32 v70, v2
	v_mov_b32_e32 v71, v2
	v_mov_b32_e32 v72, v2
	v_mov_b32_e32 v73, v2
	v_mov_b32_e32 v74, v2
	v_mov_b32_e32 v75, v2
	v_mov_b32_e32 v76, v2
	v_mov_b32_e32 v77, v2
	v_mov_b32_e32 v78, v2
	v_mov_b32_e32 v79, v2
	v_mov_b32_e32 v80, v2
	v_mov_b32_e32 v81, v2
	v_mov_b32_e32 v82, v2
	v_mov_b32_e32 v83, v2
	v_mov_b32_e32 v84, v2
	v_mov_b32_e32 v85, v2
	v_mov_b32_e32 v86, v2
	v_mov_b32_e32 v87, v2
	v_mov_b32_e32 v88, v2
	v_mov_b32_e32 v89, v2
	v_mov_b32_e32 v90, v2
	v_mov_b32_e32 v91, v2
	v_mov_b32_e32 v92, v2
	v_mov_b32_e32 v93, v2
	v_mov_b32_e32 v94, v2
	v_mov_b32_e32 v95, v2
	v_mov_b32_e32 v96, v2
	v_mov_b32_e32 v97, v2
	v_mov_b32_e32 v98, v2
	v_mov_b32_e32 v99, v2
	v_mov_b32_e32 v100, v2
	v_mov_b32_e32 v101, v2
	v_mov_b32_e32 v102, v2
	v_mov_b32_e32 v103, v2
	v_mov_b32_e32 v104, v2
	v_mov_b32_e32 v105, v2
	v_mov_b32_e32 v106, v2
	v_mov_b32_e32 v107, v2
	v_mov_b32_e32 v108, v2
	v_mov_b32_e32 v109, v2
	v_mov_b32_e32 v110, v2
	v_mov_b32_e32 v111, v2
	v_mov_b32_e32 v112, v2
	v_mov_b32_e32 v113, v2
	v_mov_b32_e32 v114, v2
	v_mov_b32_e32 v115, v2
	v_mov_b32_e32 v116, v2
	v_mov_b32_e32 v117, v2
	v_mov_b32_e32 v118, v2
	v_mov_b32_e32 v119, v2
	v_mov_b32_e32 v120, v2
	v_mov_b32_e32 v121, v2
	v_mov_b32_e32 v122, v2
	v_mov_b32_e32 v123, v2
	v_mov_b32_e32 v124, v2
	v_mov_b32_e32 v125, v2
	v_mov_b32_e32 v126, v2
	v_mov_b32_e32 v127, v2
	v_mov_b32_e32 v128, v2
	v_mov_b32_e32 v129, v2
	s_waitcnt lgkmcnt(0)
	s_barrier
	s_branch .LBB0_146
